# attention K/V global prefetch two tiles deep (two staging register sets, 10 fragment slots) on top of copy repartition
# baseline (speedup 1.0000x reference)
.LBB0_580:
	v_cndmask_b32_e64 v0, 0, 1, s[12:13]
	v_cmp_ne_u32_e64 s[0:1], 1, v0
	s_andn2_b64 vcc, exec, s[12:13]
	v_mov_b32_e32 v187, v64
	s_cbranch_vccnz .LBB0_582
	global_load_dwordx4 v[96:99], v[116:117], off
	global_load_dwordx4 v[100:103], v[118:119], off
	global_load_dwordx4 v[104:107], v[120:121], off
	global_load_dwordx4 v[108:111], v[124:125], off
	v_add_u32_e32 v0, 0x100, v172
	s_waitcnt vmcnt(3)
	ds_write_b128 v145, v[96:99]
	s_waitcnt vmcnt(2)
	ds_write_b128 v145, v[100:103] offset:64
	s_waitcnt vmcnt(1)
	ds_write_b128 v0, v[104:107] offset:16640
	s_waitcnt vmcnt(0)
	ds_write_b128 v0, v[108:111] offset:16768
	s_cmp_lt_i32 s81, 1
	s_cbranch_scc1 .LBB0_582
	s_mov_b32 s100, 0xfffe0000
	s_mov_b32 s101, -1
	v_lshl_add_u64 v[64:65], v[116:117], 0, s[100:101]
	v_lshl_add_u64 v[66:67], v[118:119], 0, s[100:101]
	s_mov_b32 s100, 0xffffff80
	v_lshl_add_u64 v[68:69], v[120:121], 0, s[100:101]
	v_lshl_add_u64 v[70:71], v[124:125], 0, s[100:101]
	global_load_dwordx4 v[234:237], v[64:65], off
	global_load_dwordx4 v[242:245], v[66:67], off
	global_load_dwordx4 v[246:249], v[68:69], off
	global_load_dwordx4 v[250:253], v[70:71], off

.LBB0_585:
	s_cmp_lt_i32 s70, s81
	s_cselect_b64 s[10:11], -1, 0
	s_mov_b32 s98, 0
	s_add_i32 s1, s70, 2
	s_cmp_le_i32 s1, s81
	s_cbranch_scc0 .Lpf_done
	s_add_i32 vcc_lo, s15, -2
	s_ashr_i32 vcc_hi, vcc_lo, 31
	s_lshl_b64 vcc, vcc, 17
	v_lshl_add_u64 v[64:65], v[112:113], 0, vcc
	s_add_i32 vcc_lo, s0, -60
	s_ashr_i32 vcc_hi, vcc_lo, 31
	s_lshl_b64 vcc, vcc, 11
	v_lshl_add_u64 v[66:67], v[112:113], 0, vcc
	s_add_i32 vcc_lo, s0, 0xffffffc0
	s_ashr_i32 vcc_hi, vcc_lo, 31
	s_lshl_b64 vcc, vcc, 1
	v_lshl_add_u64 v[68:69], v[114:115], 0, vcc
	v_lshl_add_u64 v[70:71], v[122:123], 0, vcc
	s_mov_b32 s98, 1
	s_bitcmp1_b32 s70, 0
	s_cbranch_scc1 .Lpf_issue_odd
	global_load_dwordx4 v[96:99], v[64:65], off
	global_load_dwordx4 v[100:103], v[66:67], off
	global_load_dwordx4 v[104:107], v[68:69], off
	global_load_dwordx4 v[108:111], v[70:71], off
	s_branch .Lpf_done
.Lpf_issue_odd:
	global_load_dwordx4 v[234:237], v[64:65], off
	global_load_dwordx4 v[242:245], v[66:67], off
	global_load_dwordx4 v[246:249], v[68:69], off
	global_load_dwordx4 v[250:253], v[70:71], off
.Lpf_done:
	s_cmp_gt_i32 s15, s14
	s_cbranch_scc0 .LBB0_589

.LBB0_589:
	s_bitcmp1_b32 s70, 0
	v_cvt_f32_i32_e32 v130, v190
	s_cselect_b32 s1, 0x8200, 0
	s_addk_i32 s1, 0x100
	s_cmp_eq_u32 s4, s70
	s_cbranch_scc1 .Latt_diag
	v_add_u32_e32 v127, s1, v166
	ds_read_b128 v[198:201], v127
	ds_read_b128 v[218:221], v186
	ds_read_b128 v[202:205], v127 offset:2080
	ds_read_b128 v[222:225], v186 offset:4128
	ds_read_b128 v[206:209], v127 offset:4160
	ds_read_b128 v[226:229], v186 offset:8256
	ds_read_b128 v[210:213], v127 offset:6240
	ds_read_b128 v[230:233], v186 offset:12384
	ds_read_b128 v[214:217], v127 offset:512
	v_fma_f32 v192, -v129, v130, -v188
	v_mov_b32_e32 v80, v129
	v_add3_u32 v191, s1, v167, v168
	v_fma_f32 v64, 0, v80, v192
	v_add_f32_e32 v65, v80, v192
	v_pk_fma_f32 v[66:67], v[80:81], s[84:85], v[192:193] op_sel_hi:[0,1,0]
	v_pk_fma_f32 v[68:69], v[80:81], s[86:87], v[192:193] op_sel_hi:[0,1,0]
	v_pk_fma_f32 v[70:71], v[80:81], s[88:89], v[192:193] op_sel_hi:[0,1,0]
	v_pk_fma_f32 v[72:73], v[80:81], s[90:91], v[192:193] op_sel_hi:[0,1,0]
	v_pk_fma_f32 v[74:75], v[80:81], s[92:93], v[192:193] op_sel_hi:[0,1,0]
	v_pk_fma_f32 v[76:77], v[80:81], s[94:95], v[192:193] op_sel_hi:[0,1,0]
	v_pk_fma_f32 v[78:79], v[80:81], s[96:97], v[192:193] op_sel_hi:[0,1,0]
	v_pk_fma_f32 v[94:95], v[80:81], s[22:23], v[192:193] op_sel_hi:[0,1,0]
	v_pk_fma_f32 v[92:93], v[80:81], s[74:75], v[192:193] op_sel_hi:[0,1,0]
	v_pk_fma_f32 v[90:91], v[80:81], s[76:77], v[192:193] op_sel_hi:[0,1,0]
	v_pk_fma_f32 v[88:89], v[80:81], s[24:25], v[192:193] op_sel_hi:[0,1,0]
	v_pk_fma_f32 v[86:87], v[80:81], s[26:27], v[192:193] op_sel_hi:[0,1,0]
	v_pk_fma_f32 v[84:85], v[80:81], s[72:73], v[192:193] op_sel_hi:[0,1,0]
	v_pk_fma_f32 v[82:83], v[80:81], s[18:19], v[192:193] op_sel_hi:[0,1,0]
	v_pk_fma_f32 v[80:81], v[80:81], s[34:35], v[192:193] op_sel_hi:[0,1,0]
	ds_read_b128 v[192:195], v127 offset:2592
	s_waitcnt lgkmcnt(8)
	v_mfma_f32_32x32x16_bf16 v[64:79], v[198:201], v[218:221], v[64:79]
	ds_read_b128 v[198:201], v127 offset:4672
	s_waitcnt lgkmcnt(7)
	v_mfma_f32_32x32x16_bf16 v[64:79], v[202:205], v[222:225], v[64:79]
	ds_read_b128 v[202:205], v127 offset:6752
	s_waitcnt lgkmcnt(6)
	v_mfma_f32_32x32x16_bf16 v[64:79], v[206:209], v[226:229], v[64:79]
	s_waitcnt lgkmcnt(4)
	v_mfma_f32_32x32x16_bf16 v[64:79], v[210:213], v[230:233], v[64:79]
	ds_read_b128 v[206:209], v191 offset:16640
	ds_read_b128 v[210:213], v191 offset:17152
	s_waitcnt lgkmcnt(5)
	v_mfma_f32_32x32x16_bf16 v[80:95], v[214:217], v[218:221], v[80:95]
	s_waitcnt lgkmcnt(4)
	v_mfma_f32_32x32x16_bf16 v[80:95], v[192:195], v[222:225], v[80:95]
	s_waitcnt lgkmcnt(3)
	v_mfma_f32_32x32x16_bf16 v[80:95], v[198:201], v[226:229], v[80:95]
	s_waitcnt lgkmcnt(2)
	v_mfma_f32_32x32x16_bf16 v[80:95], v[202:205], v[230:233], v[80:95]
	ds_read_b128 v[214:217], v191 offset:17664
	ds_read_b128 v[192:195], v191 offset:18176
	ds_read_b128 v[198:201], v191 offset:20768
	ds_read_b128 v[202:205], v191 offset:21280
	ds_read_b128 v[218:221], v191 offset:21792
	ds_read_b128 v[222:225], v191 offset:22304
	ds_read_b128 v[226:229], v191 offset:24896
	ds_read_b128 v[230:233], v191 offset:25408
	v_exp_f32_e32 v64, v64
	v_exp_f32_e32 v65, v65
	v_exp_f32_e32 v66, v66
	v_exp_f32_e32 v67, v67
	v_exp_f32_e32 v68, v68
	v_exp_f32_e32 v69, v69
	v_exp_f32_e32 v70, v70
	v_exp_f32_e32 v71, v71
	v_add_f32_e32 v130, v64, v65
	v_add_f32_e32 v130, v130, v66
	v_add_f32_e32 v130, v130, v67
	v_add_f32_e32 v130, v130, v68
	v_add_f32_e32 v130, v130, v69
	v_add_f32_e32 v130, v130, v70
	v_add_f32_e32 v130, v130, v71
	v_cvt_pk_bf16_f32 v64, v64, v65
	v_cvt_pk_bf16_f32 v65, v66, v67
	v_cvt_pk_bf16_f32 v66, v68, v69
	v_cvt_pk_bf16_f32 v67, v70, v71
	s_waitcnt lgkmcnt(9)
	v_exp_f32_e32 v72, v72
	v_mfma_f32_32x32x16_bf16 v[48:63], v[206:209], v[64:67], v[48:63]
	v_exp_f32_e32 v73, v73
	v_exp_f32_e32 v74, v74
	v_add_f32_e32 v130, v130, v72
	v_add_f32_e32 v130, v130, v73
	s_waitcnt lgkmcnt(8)
	v_mfma_f32_32x32x16_bf16 v[32:47], v[210:213], v[64:67], v[32:47]
	v_exp_f32_e32 v75, v75
	v_exp_f32_e32 v76, v76
	v_cvt_pk_bf16_f32 v68, v72, v73
	v_add_f32_e32 v130, v130, v74
	s_waitcnt lgkmcnt(7)
	v_mfma_f32_32x32x16_bf16 v[16:31], v[214:217], v[64:67], v[16:31]
	v_exp_f32_e32 v77, v77
	v_exp_f32_e32 v78, v78
	v_cvt_pk_bf16_f32 v69, v74, v75
	v_add_f32_e32 v130, v130, v75
	v_add_f32_e32 v130, v130, v76
	s_waitcnt lgkmcnt(6)
	v_mfma_f32_32x32x16_bf16 v[0:15], v[192:195], v[64:67], v[0:15]
	ds_read_b128 v[206:209], v191 offset:25920
	ds_read_b128 v[210:213], v191 offset:26432
	ds_read_b128 v[214:217], v191 offset:29024
	ds_read_b128 v[192:195], v191 offset:29536
	v_exp_f32_e32 v79, v79
	v_cvt_pk_bf16_f32 v70, v76, v77
	v_add_f32_e32 v130, v130, v77
	v_add_f32_e32 v130, v130, v78
	v_add_f32_e32 v130, v130, v79
	v_cvt_pk_bf16_f32 v71, v78, v79
	s_waitcnt lgkmcnt(9)
	v_exp_f32_e32 v80, v80
	v_mfma_f32_32x32x16_bf16 v[48:63], v[198:201], v[68:71], v[48:63]
	v_exp_f32_e32 v81, v81
	v_exp_f32_e32 v82, v82
	v_add_f32_e32 v130, v130, v80
	v_add_f32_e32 v130, v130, v81
	s_waitcnt lgkmcnt(8)
	v_mfma_f32_32x32x16_bf16 v[32:47], v[202:205], v[68:71], v[32:47]
	v_exp_f32_e32 v83, v83
	v_exp_f32_e32 v84, v84
	v_cvt_pk_bf16_f32 v72, v80, v81
	v_add_f32_e32 v130, v130, v82
	s_waitcnt lgkmcnt(7)
	v_mfma_f32_32x32x16_bf16 v[16:31], v[218:221], v[68:71], v[16:31]
	v_exp_f32_e32 v85, v85
	v_exp_f32_e32 v86, v86
	v_cvt_pk_bf16_f32 v73, v82, v83
	v_add_f32_e32 v130, v130, v83
	v_add_f32_e32 v130, v130, v84
	s_waitcnt lgkmcnt(6)
	v_mfma_f32_32x32x16_bf16 v[0:15], v[222:225], v[68:71], v[0:15]
	ds_read_b128 v[198:201], v191 offset:30048
	ds_read_b128 v[202:205], v191 offset:30560
	v_exp_f32_e32 v87, v87
	v_cvt_pk_bf16_f32 v74, v84, v85
	v_add_f32_e32 v130, v130, v85
	v_add_f32_e32 v130, v130, v86
	v_add_f32_e32 v130, v130, v87
	v_cvt_pk_bf16_f32 v75, v86, v87
	s_waitcnt lgkmcnt(7)
	v_exp_f32_e32 v88, v88
	v_mfma_f32_32x32x16_bf16 v[48:63], v[226:229], v[72:75], v[48:63]
	v_exp_f32_e32 v89, v89
	v_exp_f32_e32 v90, v90
	v_add_f32_e32 v130, v130, v88
	v_add_f32_e32 v130, v130, v89
	s_waitcnt lgkmcnt(6)
	v_mfma_f32_32x32x16_bf16 v[32:47], v[230:233], v[72:75], v[32:47]
	v_exp_f32_e32 v91, v91
	v_exp_f32_e32 v92, v92
	v_cvt_pk_bf16_f32 v76, v88, v89
	v_add_f32_e32 v130, v130, v90
	s_waitcnt lgkmcnt(5)
	v_mfma_f32_32x32x16_bf16 v[16:31], v[206:209], v[72:75], v[16:31]
	v_exp_f32_e32 v93, v93
	v_exp_f32_e32 v94, v94
	v_cvt_pk_bf16_f32 v77, v90, v91
	v_add_f32_e32 v130, v130, v91
	v_add_f32_e32 v130, v130, v92
	s_waitcnt lgkmcnt(4)
	v_mfma_f32_32x32x16_bf16 v[0:15], v[210:213], v[72:75], v[0:15]
	v_exp_f32_e32 v95, v95
	v_cvt_pk_bf16_f32 v78, v92, v93
	v_add_f32_e32 v130, v130, v93
	v_add_f32_e32 v130, v130, v94
	v_add_f32_e32 v130, v130, v95
	v_cvt_pk_bf16_f32 v79, v94, v95
	s_and_b64 vcc, exec, s[10:11]
	s_cbranch_vccz .Latt_nostore
	s_sub_i32 s1, 0x8400, s1
	v_add_u32_e32 v127, s1, v170
	v_add_u32_e32 v191, s1, v172
	s_bitcmp1_b32 s70, 0
	s_cbranch_scc1 .Lstf_a
	s_cmp_eq_u32 s98, 0
	s_cbranch_scc1 .Lstf_bw0
	s_waitcnt vmcnt(4)
	s_branch .Lstf_bgo

.Lstf_bgo:
	ds_write_b128 v127, v[234:237]
	ds_write_b128 v127, v[242:245] offset:64
	ds_write_b128 v191, v[246:249] offset:16640
	ds_write_b128 v191, v[250:253] offset:16768
	s_branch .Lstf_end
.Lstf_a:
	s_cmp_eq_u32 s98, 0
	s_cbranch_scc1 .Lstf_aw0
	s_waitcnt vmcnt(4)
	s_branch .Lstf_ago

.Lstf_ago:
	ds_write_b128 v127, v[96:99]
	ds_write_b128 v127, v[100:103] offset:64
	ds_write_b128 v191, v[104:107] offset:16640
	ds_write_b128 v191, v[108:111] offset:16768
.Lstf_end:
	s_waitcnt lgkmcnt(7)
	v_mfma_f32_32x32x16_bf16 v[48:63], v[214:217], v[76:79], v[48:63]
	s_waitcnt lgkmcnt(6)
	v_mfma_f32_32x32x16_bf16 v[32:47], v[192:195], v[76:79], v[32:47]
	s_waitcnt lgkmcnt(5)
	v_mfma_f32_32x32x16_bf16 v[16:31], v[198:201], v[76:79], v[16:31]
	s_waitcnt lgkmcnt(4)
	v_mfma_f32_32x32x16_bf16 v[0:15], v[202:205], v[76:79], v[0:15]
	v_add_f32_e32 v150, v150, v130
	s_add_i32 s70, s70, 1
	s_branch .LBB0_584
.Latt_nostore:
	s_waitcnt lgkmcnt(3)
	v_mfma_f32_32x32x16_bf16 v[48:63], v[214:217], v[76:79], v[48:63]
	s_waitcnt lgkmcnt(2)
	v_mfma_f32_32x32x16_bf16 v[32:47], v[192:195], v[76:79], v[32:47]
	s_waitcnt lgkmcnt(1)
	v_mfma_f32_32x32x16_bf16 v[16:31], v[198:201], v[76:79], v[16:31]
	s_waitcnt lgkmcnt(0)
	v_mfma_f32_32x32x16_bf16 v[0:15], v[202:205], v[76:79], v[0:15]
	v_add_f32_e32 v150, v150, v130
	s_add_i32 s70, s70, 1
	s_branch .LBB0_584

.LBB0_592:
	s_bitcmp1_b32 s70, 0
	s_cselect_b32 s1, 0x8200, 0
	s_addk_i32 s1, 0x100
	v_add_u32_e32 v64, s1, v170
	v_add_u32_e32 v65, s1, v172
	s_bitcmp1_b32 s70, 0
	s_cbranch_scc1 .Lstg_a
	s_cmp_eq_u32 s98, 0
	s_cbranch_scc1 .Lstg_bw0
	s_waitcnt vmcnt(4)
	s_branch .Lstg_bgo

.Lstg_bgo:
	ds_write_b128 v64, v[96:99]
	ds_write_b128 v64, v[100:103] offset:64
	ds_write_b128 v65, v[104:107] offset:16640
	ds_write_b128 v65, v[108:111] offset:16768
	s_branch .Lstg_end

.Lstg_ago:
	ds_write_b128 v64, v[234:237]
	ds_write_b128 v64, v[242:245] offset:64
	ds_write_b128 v65, v[246:249] offset:16640
	ds_write_b128 v65, v[250:253] offset:16768
.Lstg_end:
	s_branch .LBB0_584
.LBB0_593:
	v_mov_b32_e32 v14, v15
	v_mov_b32_e32 v13, v15
	v_mov_b32_e32 v12, v15
	v_mov_b32_e32 v11, v15
	v_mov_b32_e32 v10, v15
	v_mov_b32_e32 v9, v15
	v_mov_b32_e32 v8, v15
	v_mov_b32_e32 v7, v15
	v_mov_b32_e32 v6, v15
	v_mov_b32_e32 v5, v15
	v_mov_b32_e32 v4, v15
	v_mov_b32_e32 v3, v15
	v_mov_b32_e32 v2, v15
	v_mov_b32_e32 v1, v15
	v_mov_b32_e32 v0, v15
	v_mov_b32_e32 v31, v15
	v_mov_b32_e32 v30, v15
	v_mov_b32_e32 v29, v15
	v_mov_b32_e32 v28, v15
	v_mov_b32_e32 v27, v15
	v_mov_b32_e32 v26, v15
	v_mov_b32_e32 v25, v15
	v_mov_b32_e32 v24, v15
	v_mov_b32_e32 v23, v15
	v_mov_b32_e32 v22, v15
	v_mov_b32_e32 v21, v15
	v_mov_b32_e32 v20, v15
	v_mov_b32_e32 v19, v15
	v_mov_b32_e32 v18, v15
	v_mov_b32_e32 v17, v15
	v_mov_b32_e32 v16, v15
	v_mov_b32_e32 v47, v15
	v_mov_b32_e32 v46, v15
	v_mov_b32_e32 v45, v15
	v_mov_b32_e32 v44, v15
	v_mov_b32_e32 v43, v15
	v_mov_b32_e32 v42, v15
	v_mov_b32_e32 v41, v15
	v_mov_b32_e32 v40, v15
	v_mov_b32_e32 v39, v15
	v_mov_b32_e32 v38, v15
	v_mov_b32_e32 v37, v15
	v_mov_b32_e32 v36, v15
	v_mov_b32_e32 v35, v15
	v_mov_b32_e32 v34, v15
	v_mov_b32_e32 v33, v15
	v_mov_b32_e32 v32, v15
	v_mov_b32_e32 v63, v15
	v_mov_b32_e32 v62, v15
	v_mov_b32_e32 v61, v15
	v_mov_b32_e32 v60, v15
	v_mov_b32_e32 v59, v15
	v_mov_b32_e32 v58, v15
	v_mov_b32_e32 v57, v15
	v_mov_b32_e32 v56, v15
	v_mov_b32_e32 v55, v15
	v_mov_b32_e32 v54, v15
	v_mov_b32_e32 v53, v15
	v_mov_b32_e32 v52, v15
	v_mov_b32_e32 v51, v15
	v_mov_b32_e32 v50, v15
	v_mov_b32_e32 v49, v15
	v_mov_b32_e32 v48, v15
	v_mov_b32_e32 v150, v15

	.amdhsa_kernel _Z10fwd_kernel4Args
		.amdhsa_group_segment_fixed_size 256
		.amdhsa_private_segment_fixed_size 0
		.amdhsa_kernarg_size 472
		.amdhsa_user_sgpr_count 2
		.amdhsa_user_sgpr_dispatch_ptr 0
		.amdhsa_user_sgpr_queue_ptr 0
		.amdhsa_user_sgpr_kernarg_segment_ptr 1
		.amdhsa_user_sgpr_dispatch_id 0
		.amdhsa_user_sgpr_kernarg_preload_length 0
		.amdhsa_user_sgpr_kernarg_preload_offset 0
		.amdhsa_user_sgpr_private_segment_size 0
		.amdhsa_uses_dynamic_stack 0
		.amdhsa_enable_private_segment 0
		.amdhsa_system_sgpr_workgroup_id_x 1
		.amdhsa_system_sgpr_workgroup_id_y 0
		.amdhsa_system_sgpr_workgroup_id_z 0
		.amdhsa_system_sgpr_workgroup_info 0
		.amdhsa_system_vgpr_workitem_id 2
		.amdhsa_next_free_vgpr 256
		.amdhsa_next_free_sgpr 102
		.amdhsa_accum_offset 256
		.amdhsa_reserve_vcc 1
		.amdhsa_float_round_mode_32 0
		.amdhsa_float_round_mode_16_64 0
		.amdhsa_float_denorm_mode_32 3
		.amdhsa_float_denorm_mode_16_64 3
		.amdhsa_dx10_clamp 1
		.amdhsa_ieee_mode 1
		.amdhsa_fp16_overflow 0
		.amdhsa_tg_split 0
		.amdhsa_exception_fp_ieee_invalid_op 0
		.amdhsa_exception_fp_denorm_src 0
		.amdhsa_exception_fp_ieee_div_zero 0
		.amdhsa_exception_fp_ieee_overflow 0
		.amdhsa_exception_fp_ieee_underflow 0
		.amdhsa_exception_fp_ieee_inexact 0
		.amdhsa_exception_int_div_zero 0
	.end_amdhsa_kernel

amdhsa.kernels:
  - .agpr_count:     0
    .args:
      - .offset:         0
        .size:           216
        .value_kind:     by_value
      - .offset:         216
        .size:           4
        .value_kind:     hidden_block_count_x
      - .offset:         220
        .size:           4
        .value_kind:     hidden_block_count_y
      - .offset:         224
        .size:           4
        .value_kind:     hidden_block_count_z
      - .offset:         228
        .size:           2
        .value_kind:     hidden_group_size_x
      - .offset:         230
        .size:           2
        .value_kind:     hidden_group_size_y
      - .offset:         232
        .size:           2
        .value_kind:     hidden_group_size_z
      - .offset:         234
        .size:           2
        .value_kind:     hidden_remainder_x
      - .offset:         236
        .size:           2
        .value_kind:     hidden_remainder_y
      - .offset:         238
        .size:           2
        .value_kind:     hidden_remainder_z
      - .offset:         256
        .size:           8
        .value_kind:     hidden_global_offset_x
      - .offset:         264
        .size:           8
        .value_kind:     hidden_global_offset_y
      - .offset:         272
        .size:           8
        .value_kind:     hidden_global_offset_z
      - .offset:         280
        .size:           2
        .value_kind:     hidden_grid_dims
      - .offset:         304
        .size:           8
        .value_kind:     hidden_multigrid_sync_arg
      - .offset:         336
        .size:           4
        .value_kind:     hidden_dynamic_lds_size
    .group_segment_fixed_size: 256
    .kernarg_segment_align: 8
    .kernarg_segment_size: 472
    .language:       OpenCL C
    .language_version:
      - 2
      - 0
    .max_flat_workgroup_size: 512
    .name:           _Z10fwd_kernel4Args
    .private_segment_fixed_size: 0
    .sgpr_count:     108
    .sgpr_spill_count: 103
    .symbol:         _Z10fwd_kernel4Args.kd
    .uniform_work_group_size: 1
    .uses_dynamic_stack: false
    .vgpr_count:     256
    .vgpr_spill_count: 0
    .wavefront_size: 64
